# P2: the inverse-by-doubling loop of the 16-token sample units applies only the non-zero factors M..M^8 (bit-identical); P3 bias-table loads issued together
# baseline (speedup 1.0000x reference)
; DI unsigned pack2(float lo, float hi) { f32x2_t v = {lo, hi}; bf16x2_t b = __builtin_convertvector(v, bf16x2_t); return __builtin_bit_cast(unsigned, b); }
; DI void phase_rwkv_prep(const Params& p, char* lds) {
;     ...
;                 if (i & 1) { pAt[i >> 1] = pack2(hAt, vAt); pV[i >> 1] = pack2(hV, xv); pKb[i >> 1] = pack2(hKb, vKb); pBb[i >> 1] = pack2(hBb, vBb); }
;                 else { hAt = vAt; hV = xv; hKb = vKb; hBb = vBb; }
;             }
;             if (lane < 16) bonus[(size_t)u * 64 + 16 * tg + lane] = mybon;
;             __syncthreads();
; #pragma unroll
;             for (int half = 0; half < 2; ++half) { const int o = swz(j, 2 * tg + half);
;                 *(uint4*)(R4 + o) = (uint4){pAt[4 * half], pAt[4 * half + 1], pAt[4 * half + 2], pAt[4 * half + 3]};
;                 *(uint4*)(R5 + o) = (uint4){pV[4 * half], pV[4 * half + 1], pV[4 * half + 2], pV[4 * half + 3]};
;                 *(uint4*)(R6 + o) = (uint4){pKb[4 * half], pKb[4 * half + 1], pKb[4 * half + 2], pKb[4 * half + 3]};
;                 *(uint4*)(R7 + o) = (uint4){pBb[4 * half], pBb[4 * half + 1], pBb[4 * half + 2], pBb[4 * half + 3]}; }
;         }
;         __syncthreads();
;         f32x16 z16;
; #pragma unroll
;         for (int e = 0; e < 16; ++e) z16[e] = 0.f;
;         f32x16 aN = mmq(R2, R0, qm, qn, z16, lane);
;         f32x16 aKa = mmq(R3, R0, qm, qn, z16, lane);
;         f32x16 aW1 = mmq(R2, R1, qm, qn, z16, lane);
;         f32x16 aKr = mmq(R3, R1, qm, qn, z16, lane);
;         {
;             const int n = 32 * qn + r;
; #pragma unroll
;             for (int e = 0; e < 16; ++e) { const int m = 32 * qm + (e & 3) + 8 * (e >> 2) + 4 * h5;
;                 if (!(m < n)) { aN[e] = 0.f; aKa[e] = 0.f; } if (!(m <= n)) { aW1[e] = 0.f; aKr[e] = 0.f; } }
;     ...
;         for (int it = 0; it < 6; ++it) {
;             aW1 = mmq(R0, R8, qm, qn, aW1, lane);
;             aW2 = mmq(R0, R7, qm, qn, aW2, lane);
;             if (it < 5) aN = mmq(R0, R2, qm, qn, z16, lane);
;             __syncthreads();
;             st_nat(R8, aW1, qm, qn, lane); st_nat(R7, aW2, qm, qn, lane);
;             if (it < 5) { st_sc(R0, aN, qm, qn, lane); st_nat(R2, aN, qm, qn, lane); }
;             __syncthreads();
;         }
.LBB0_309:
	s_or_b64 exec, exec, s[4:5]
	v_mul_f32_e32 v2, v3, v110
	v_mul_f32_e32 v22, v111, v2
	v_mul_f32_e32 v2, v108, v2
	v_mul_f32_e32 v8, v8, v5
	v_cvt_pk_bf16_f32 v47, v2, v8
	v_mul_f32_e32 v2, v3, v106
	v_pk_mul_f32 v[4:5], v[4:5], v[4:5] op_sel_hi:[0,1]
	v_cvt_pk_bf16_f32 v23, v109, v9
	v_mul_f32_e32 v8, v107, v2
	v_mul_f32_e32 v2, v104, v2
	v_mul_f32_e32 v9, v44, v21
	v_cvt_pk_bf16_f32 v109, v22, v5
	v_pk_mul_f32 v[4:5], v[20:21], v[20:21] op_sel_hi:[0,1]
	v_cvt_pk_bf16_f32 v22, v105, v46
	v_cvt_pk_bf16_f32 v46, v2, v9
	v_mul_f32_e32 v2, v3, v102
	v_cvt_pk_bf16_f32 v108, v8, v5
	v_mul_f32_e32 v8, v103, v2
	v_mul_f32_e32 v2, v100, v2
	v_mul_f32_e32 v9, v57, v19
	v_pk_mul_f32 v[4:5], v[18:19], v[18:19] op_sel_hi:[0,1]
	v_cvt_pk_bf16_f32 v45, v2, v9
	v_mul_f32_e32 v2, v3, v98
	v_cvt_pk_bf16_f32 v107, v8, v5
	v_mul_f32_e32 v8, v99, v2
	v_mul_f32_e32 v2, v96, v2
	v_mul_f32_e32 v9, v83, v17
	v_pk_mul_f32 v[4:5], v[16:17], v[16:17] op_sel_hi:[0,1]
	v_cvt_pk_bf16_f32 v44, v2, v9
	v_mul_f32_e32 v2, v3, v90
	v_cvt_pk_bf16_f32 v106, v8, v5
	v_mul_f32_e32 v8, v91, v2
	v_mul_f32_e32 v2, v88, v2
	v_mul_f32_e32 v9, v93, v15
	v_pk_mul_f32 v[4:5], v[14:15], v[14:15] op_sel_hi:[0,1]
	v_cvt_pk_bf16_f32 v83, v2, v9
	v_mul_f32_e32 v2, v3, v78
	v_cvt_pk_bf16_f32 v25, v80, v87
	v_cvt_pk_bf16_f32 v87, v8, v5
	v_mul_f32_e32 v8, v79, v2
	v_mul_f32_e32 v2, v70, v2
	v_mul_f32_e32 v9, v81, v13
	v_pk_mul_f32 v[4:5], v[12:13], v[12:13] op_sel_hi:[0,1]
	v_cvt_pk_bf16_f32 v14, v77, v82
	v_cvt_pk_bf16_f32 v82, v2, v9
	v_mul_f32_e32 v2, v3, v51
	v_cvt_pk_bf16_f32 v20, v97, v86
	v_cvt_pk_bf16_f32 v86, v8, v5
	v_mul_f32_e32 v8, v52, v2
	v_mul_f32_e32 v2, v49, v2
	v_mul_f32_e32 v9, v54, v11
	v_pk_mul_f32 v[4:5], v[10:11], v[10:11] op_sel_hi:[0,1]
	v_cvt_pk_bf16_f32 v81, v2, v9
	v_mul_f32_e32 v2, v3, v37
	v_cvt_pk_bf16_f32 v19, v85, v84
	v_cvt_pk_bf16_f32 v85, v8, v5
	v_mul_f32_e32 v4, v38, v2
	v_mul_f32_e32 v5, v34, v2
	v_pk_mul_f32 v[2:3], v[6:7], v[6:7] op_sel_hi:[0,1]
	s_lshl_b32 s0, s14, 1
	v_cvt_pk_bf16_f32 v84, v4, v3
	v_xor_b32_e32 v3, s0, v68
	v_lshlrev_b32_e32 v2, 7, v62
	v_lshlrev_b32_e32 v3, 4, v3
	v_cvt_pk_bf16_f32 v15, v89, v94
	v_cvt_pk_bf16_f32 v13, v50, v56
	v_mul_f32_e32 v8, v39, v7
	v_cvt_pk_bf16_f32 v12, v36, v41
	v_add3_u32 v3, v3, v2, 0
	v_cvt_pk_bf16_f32 v18, v64, v63
	v_cvt_pk_bf16_f32 v17, v43, v42
	v_cvt_pk_bf16_f32 v16, v31, v30
	v_cvt_pk_bf16_f32 v80, v5, v8
	s_waitcnt lgkmcnt(0)
	s_barrier
	ds_write_b128 v3, v[12:15] offset:32768
	ds_write_b128 v3, v[16:19] offset:40960
	ds_write_b128 v3, v[80:83] offset:49152
	ds_write_b128 v3, v[84:87] offset:57344
	v_bitop3_b32 v3, s0, v68, 1 bitop3:0x36
	v_and_b32_e32 v6, 0xf80, v2
	v_readlane_b32 s0, v236, 36
	v_lshlrev_b32_e32 v3, 4, v3
	v_add3_u32 v3, v3, v2, 0
	v_or_b32_e32 v42, s0, v6
	v_or_b32_e32 v2, v61, v42
	v_cvt_pk_bf16_f32 v26, v53, v76
	v_cvt_pk_bf16_f32 v21, v101, v65
	v_add_u32_e32 v76, 0, v2
	v_cvt_pk_bf16_f32 v27, v40, v48
	v_cvt_pk_bf16_f32 v24, v92, v95
	ds_write_b128 v3, v[20:23] offset:32768
	ds_write_b128 v3, v[24:27] offset:40960
	ds_write_b128 v3, v[44:47] offset:49152
	ds_write_b128 v3, v[106:109] offset:57344
	s_waitcnt lgkmcnt(0)
	s_barrier
	ds_read_b128 v[2:5], v76 offset:16384
	v_readlane_b32 s0, v236, 35
	v_or_b32_e32 v10, v60, v42
	v_add_u32_e32 v77, 0, v10
	v_lshl_or_b32 v70, s0, 12, v6
	v_or_b32_e32 v90, v70, v61
	v_add_u32_e32 v78, 0, v90
	ds_read_b128 v[6:9], v78
	ds_read_b128 v[10:13], v77 offset:16384
	ds_read_b128 v[14:17], v76 offset:24576
	ds_read_b128 v[84:87], v78 offset:8192
	s_waitcnt lgkmcnt(3)
	v_mfma_f32_32x32x16_bf16 v[18:33], v[2:5], v[6:9], 0
	v_or_b32_e32 v91, v60, v70
	v_or_b32_e32 v38, v59, v42
	v_or_b32_e32 v92, v59, v70
	v_or_b32_e32 v42, v58, v42
	v_or_b32_e32 v93, v58, v70
	v_add_u32_e32 v80, 0, v91
	ds_read_b128 v[34:37], v80
	s_waitcnt lgkmcnt(2)
	v_mfma_f32_32x32x16_bf16 v[50:65], v[14:17], v[6:9], 0
	v_add_u32_e32 v79, 0, v38
	ds_read_b128 v[94:97], v79 offset:16384
	ds_read_b128 v[98:101], v77 offset:24576
	ds_read_b128 v[102:105], v80 offset:8192
	v_add_u32_e32 v82, 0, v92
	ds_read_b128 v[38:41], v82
	v_add_u32_e32 v81, 0, v42
	ds_read_b128 v[106:109], v81 offset:16384
	ds_read_b128 v[110:113], v79 offset:24576
	ds_read_b128 v[114:117], v82 offset:8192
	v_add_u32_e32 v83, 0, v93
	s_waitcnt lgkmcnt(7)
	v_mfma_f32_32x32x16_bf16 v[18:33], v[10:13], v[34:37], v[18:33]
	ds_read_b128 v[42:45], v83
	ds_read_b128 v[118:121], v81 offset:24576
	ds_read_b128 v[122:125], v83 offset:8192
	v_lshlrev_b32_e32 v69, 2, v69
	v_readlane_b32 s0, v236, 37
	s_lshl_b32 s2, s51, 2
	s_cmp_eq_u32 s50, 16
	s_cselect_b32 s3, 3, 5
	s_waitcnt lgkmcnt(8)
	v_mfma_f32_32x32x16_bf16 v[50:65], v[98:101], v[34:37], v[50:65]
	s_waitcnt lgkmcnt(6)
	v_mfma_f32_32x32x16_bf16 v[18:33], v[94:97], v[38:41], v[18:33]
	s_waitcnt lgkmcnt(4)
	v_mfma_f32_32x32x16_bf16 v[50:65], v[110:113], v[38:41], v[50:65]
	s_waitcnt lgkmcnt(2)
	v_mfma_f32_32x32x16_bf16 v[18:33], v[106:109], v[42:45], v[18:33]
	s_waitcnt lgkmcnt(1)
	v_mfma_f32_32x32x16_bf16 v[50:65], v[118:121], v[42:45], v[50:65]
	v_mfma_f32_32x32x16_bf16 v[34:49], v[2:5], v[84:87], 0
	v_mfma_f32_32x32x16_bf16 v[34:49], v[10:13], v[102:105], v[34:49]
	v_mfma_f32_32x32x16_bf16 v[2:17], v[14:17], v[84:87], 0
	v_or_b32_e32 v84, s92, v69
	v_cmp_lt_i32_e32 vcc, v84, v74
	v_or_b32_e32 v85, s0, v69
	v_readlane_b32 s0, v236, 38
	v_cmp_gt_i32_e64 s[4:5], v85, v74
	v_mfma_f32_32x32x16_bf16 v[34:49], v[94:97], v[114:117], v[34:49]
	s_nop 2
	v_cndmask_b32_e32 v94, 0, v50, vcc
	v_cndmask_b32_e32 v50, 0, v18, vcc
	v_cmp_lt_i32_e32 vcc, v85, v74
	s_nop 1
	v_cndmask_b32_e32 v95, 0, v51, vcc
	v_or_b32_e32 v51, s0, v69
	v_mfma_f32_32x32x16_bf16 v[2:17], v[98:101], v[102:105], v[2:17]
	v_readlane_b32 s0, v236, 17
	v_cndmask_b32_e32 v104, 0, v19, vcc
	v_cmp_lt_i32_e64 s[6:7], v51, v74
	v_or_b32_e32 v86, s0, v69
	v_readlane_b32 s0, v236, 14
	v_cmp_lt_i32_e64 s[8:9], v86, v74
	v_cndmask_b32_e64 v52, 0, v52, s[6:7]
	v_or_b32_e32 v87, s0, v69
	v_readlane_b32 s0, v236, 39
	s_waitcnt lgkmcnt(0)
; DI void phase_rwkv_prep(const Params& p, char* lds) {
;     ...
;         {
;             const int n = 32 * qn + r;
; #pragma unroll
;             for (int e = 0; e < 16; ++e) { const int m = 32 * qm + (e & 3) + 8 * (e >> 2) + 4 * h5;
;                 if (!(m < n)) { aN[e] = 0.f; aKa[e] = 0.f; } if (!(m <= n)) { aW1[e] = 0.f; aKr[e] = 0.f; } }
;         }
;         f32x16 aW2 = ld_nat(R7, qm, qn, lane);
;         __syncthreads();
	v_mfma_f32_32x32x16_bf16 v[34:49], v[106:109], v[122:125], v[34:49]
	v_cndmask_b32_e64 v53, 0, v53, s[8:9]
	v_or_b32_e32 v88, s0, v69
	v_readlane_b32 s0, v236, 15
	v_cmp_lt_i32_e64 s[10:11], v87, v74
	v_cmp_lt_i32_e64 s[12:13], v88, v74
	v_or_b32_e32 v89, s0, v69
	v_readlane_b32 s0, v236, 13
	v_mfma_f32_32x32x16_bf16 v[2:17], v[110:113], v[114:117], v[2:17]
	s_nop 3
	v_cndmask_b32_e64 v19, v35, 0, s[4:5]
	v_or_b32_e32 v96, s0, v69
	v_readlane_b32 s0, v236, 12
	v_xor_b32_e32 v35, s2, v68
	v_cmp_lt_i32_e64 s[14:15], v89, v74
	v_or_b32_e32 v97, s0, v69
	v_readlane_b32 s0, v236, 40
	v_mfma_f32_32x32x16_bf16 v[2:17], v[118:121], v[122:125], v[2:17]
	v_lshl_add_u32 v119, v35, 4, v70
	v_or_b32_e32 v98, s0, v69
	v_readlane_b32 s0, v236, 16
	v_bitop3_b32 v35, s2, v68, 1 bitop3:0x36
	v_lshl_add_u32 v120, v35, 4, v70
	v_or_b32_e32 v99, s0, v69
	v_readlane_b32 s0, v236, 41
	v_bitop3_b32 v35, s2, v68, 2 bitop3:0x36
	v_lshl_add_u32 v121, v35, 4, v70
	v_or_b32_e32 v100, s0, v69
	v_readlane_b32 s0, v236, 42
	v_bitop3_b32 v35, s2, v68, 3 bitop3:0x36
	v_and_b32_e32 v68, 4, v67
	v_or_b32_e32 v101, s0, v69
	v_readlane_b32 s0, v236, 43
	v_or_b32_e32 v108, s92, v68
	v_lshrrev_b32_e32 v68, 1, v68
	v_or_b32_e32 v102, s0, v69
	v_readlane_b32 s0, v236, 44
	v_cndmask_b32_e64 v56, 0, v56, s[14:15]
	v_cndmask_b32_e64 v111, 0, v24, s[14:15]
	v_or_b32_e32 v103, s0, v69
	v_readlane_b32 s0, v236, 45
	v_cmp_gt_i32_e64 s[14:15], v89, v74
	v_cmp_lt_i32_e64 s[16:17], v96, v74
	v_or_b32_e32 v69, s0, v69
	v_cmp_gt_i32_e64 s[0:1], v84, v74
	v_cmp_lt_i32_e64 s[22:23], v99, v74
	v_cmp_lt_i32_e64 s[24:25], v100, v74
	v_cndmask_b32_e64 v18, v34, 0, s[0:1]
	v_lshrrev_b32_e32 v34, 2, v66
	v_and_or_b32 v66, v66, 24, s33
	v_lshrrev_b32_e32 v109, 3, v66
	v_and_b32_e32 v66, 14, v75
	v_and_b32_e32 v89, 8, v34
	v_add_u32_e32 v75, 0, v66
	v_lshlrev_b32_e32 v66, 7, v108
	v_xor_b32_e32 v68, v109, v68
	v_cmp_lt_i32_e64 s[30:31], v103, v74
	v_add_u32_e32 v34, 0, v89
	v_lshl_or_b32 v66, v68, 4, v66
	v_cndmask_b32_e64 v57, 0, v57, s[16:17]
	v_cndmask_b32_e64 v60, 0, v60, s[22:23]
	v_cndmask_b32_e64 v61, 0, v61, s[24:25]
	v_cndmask_b32_e64 v64, 0, v64, s[30:31]
	v_cmp_lt_i32_e64 s[36:37], v69, v74
	v_cndmask_b32_e64 v105, 0, v20, s[6:7]
	v_cmp_gt_i32_e64 s[6:7], v51, v74
	v_cndmask_b32_e64 v51, 0, v21, s[8:9]
	v_cmp_gt_i32_e64 s[8:9], v86, v74
	v_cndmask_b32_e64 v112, 0, v25, s[16:17]
	v_cmp_gt_i32_e64 s[16:17], v96, v74
	v_cndmask_b32_e64 v114, 0, v28, s[22:23]
	v_cmp_gt_i32_e64 s[22:23], v99, v74
	v_cndmask_b32_e64 v115, 0, v29, s[24:25]
	v_cmp_gt_i32_e64 s[24:25], v100, v74
	v_cndmask_b32_e64 v118, 0, v32, s[30:31]
	v_cmp_gt_i32_e64 s[30:31], v103, v74
	v_cmp_gt_i32_e32 vcc, v69, v74
	v_add_u32_e32 v85, v34, v119
	v_add_u32_e32 v86, v34, v120
	v_lshl_add_u32 v122, v35, 4, v70
	v_add_u32_e32 v66, v75, v66
	v_cvt_pk_bf16_f32 v68, v104, s0
	v_cndmask_b32_e64 v54, 0, v54, s[10:11]
	v_cndmask_b32_e64 v55, 0, v55, s[12:13]
	v_cmp_lt_i32_e64 s[18:19], v97, v74
	v_cndmask_b32_e64 v20, v36, 0, s[6:7]
	v_cndmask_b32_e64 v21, v37, 0, s[8:9]
	v_cndmask_b32_e64 v106, 0, v22, s[10:11]
	v_cmp_gt_i32_e64 s[10:11], v87, v74
	v_cndmask_b32_e64 v110, 0, v23, s[12:13]
	v_cmp_gt_i32_e64 s[12:13], v88, v74
	v_cndmask_b32_e64 v24, v40, 0, s[14:15]
	v_cndmask_b32_e64 v25, v41, 0, s[16:17]
	v_cndmask_b32_e64 v28, v44, 0, s[22:23]
	v_cndmask_b32_e64 v29, v45, 0, s[24:25]
	v_cndmask_b32_e64 v32, v48, 0, s[30:31]
	v_cndmask_b32_e64 v103, 0, v33, s[36:37]
	v_cndmask_b32_e64 v33, v49, 0, vcc
	ds_read_b64 v[36:37], v85 offset:57344
	v_add_u32_e32 v87, v34, v121
	v_add_u32_e32 v88, v34, v122
	ds_read_b64 v[40:41], v86 offset:57344
	ds_read_b64 v[44:45], v87 offset:57344
	ds_read_b64 v[48:49], v88 offset:57344
	s_waitcnt lgkmcnt(0)
	s_barrier
; DI void phase_rwkv_prep(const Params& p, char* lds) {
;     ...
;         f32x16 aW2 = ld_nat(R7, qm, qn, lane);
;         __syncthreads();
;         st_sc(R0, aN, qm, qn, lane);
;         st_nat(R2, aN, qm, qn, lane);
;         st_sc(R3, aKa, qm, qn, lane);
;         st_nat(R8, aW1, qm, qn, lane);
;         __syncthreads();
	ds_write_b16 v66, v68 offset:128
	v_or_b32_e32 v68, 2, v108
	v_cndmask_b32_e64 v58, 0, v58, s[18:19]
	v_cndmask_b32_e64 v96, 0, v26, s[18:19]
	v_cmp_gt_i32_e64 s[18:19], v97, v74
	v_lshlrev_b32_e32 v97, 7, v68
	v_lshrrev_b32_e32 v68, 1, v68
	v_or_b32_e32 v123, s92, v67
	v_bitop3_b32 v68, v68, v109, 3 bitop3:0x6c
	v_or_b32_e32 v67, 3, v123
	v_lshl_or_b32 v68, v68, 4, v97
	v_lshlrev_b32_e32 v97, 7, v67
	v_lshrrev_b32_e32 v67, 1, v67
	v_cvt_pk_bf16_f32 v69, v50, s0
	v_bitop3_b32 v67, v67, v109, 3 bitop3:0x6c
	ds_write_b16 v66, v69
	v_cvt_pk_bf16_f32 v69, v105, s0
	v_add_u32_e32 v68, v75, v68
	v_lshl_or_b32 v67, v67, 4, v97
	ds_write_b16 v68, v69
	v_cvt_pk_bf16_f32 v69, v51, s0
	v_add_u32_e32 v67, v75, v67
	v_cmp_lt_i32_e64 s[20:21], v98, v74
	ds_write_b16 v67, v69
	v_or_b32_e32 v69, 8, v108
	v_cndmask_b32_e64 v59, 0, v59, s[20:21]
	v_cndmask_b32_e64 v113, 0, v27, s[20:21]
	v_cmp_gt_i32_e64 s[20:21], v98, v74
	v_lshlrev_b32_e32 v98, 7, v69
	v_lshrrev_b32_e32 v69, 1, v69
	v_bitop3_b32 v69, v69, v109, 6 bitop3:0x6c
	v_lshl_or_b32 v69, v69, 4, v98
	v_cvt_pk_bf16_f32 v97, v106, s0
	v_add_u32_e32 v69, v75, v69
	ds_write_b16 v69, v97
	v_or_b32_e32 v97, 9, v108
	v_lshlrev_b32_e32 v99, 7, v97
	v_lshrrev_b32_e32 v97, 1, v97
	v_bitop3_b32 v97, v97, v109, 6 bitop3:0x6c
	v_lshl_or_b32 v97, v97, 4, v99
	v_cvt_pk_bf16_f32 v98, v110, s0
	v_add_u32_e32 v97, v75, v97
	ds_write_b16 v97, v98
	v_or_b32_e32 v98, 10, v108
	v_lshlrev_b32_e32 v100, 7, v98
	v_lshrrev_b32_e32 v98, 1, v98
	v_bitop3_b32 v98, v98, v109, 7 bitop3:0x6c
	v_lshl_or_b32 v98, v98, 4, v100
	v_cvt_pk_bf16_f32 v99, v111, s0
	v_add_u32_e32 v98, v75, v98
	v_cmp_lt_i32_e64 s[26:27], v101, v74
	ds_write_b16 v98, v99
	v_or_b32_e32 v99, 11, v123
	v_cndmask_b32_e64 v62, 0, v62, s[26:27]
	v_cndmask_b32_e64 v116, 0, v30, s[26:27]
	v_cmp_gt_i32_e64 s[26:27], v101, v74
	v_lshlrev_b32_e32 v101, 7, v99
	v_lshrrev_b32_e32 v99, 1, v99
	v_bitop3_b32 v99, v99, v109, 7 bitop3:0x6c
	v_lshl_or_b32 v99, v99, 4, v101
	v_cvt_pk_bf16_f32 v100, v112, s0
	v_add_u32_e32 v99, v75, v99
	ds_write_b16 v99, v100
	v_cvt_pk_bf16_f32 v100, v96, s0
	ds_write_b16 v66, v100 offset:2048
	v_cvt_pk_bf16_f32 v100, v113, s0
	v_cmp_lt_i32_e64 s[28:29], v102, v74
	ds_write_b16 v66, v100 offset:2176
	v_or_b32_e32 v100, 18, v108
	v_cndmask_b32_e64 v63, 0, v63, s[28:29]
	v_cndmask_b32_e64 v117, 0, v31, s[28:29]
	v_cmp_gt_i32_e64 s[28:29], v102, v74
	v_lshlrev_b32_e32 v102, 7, v100
	v_lshrrev_b32_e32 v100, 1, v100
	v_bitop3_b32 v100, v100, v109, 3 bitop3:0x6c
	v_lshl_or_b32 v100, v100, 4, v102
	v_cvt_pk_bf16_f32 v101, v114, s0
	v_add_u32_e32 v100, v75, v100
	ds_write_b16 v100, v101
	v_or_b32_e32 v101, 19, v123
	v_lshlrev_b32_e32 v107, 7, v101
	v_lshrrev_b32_e32 v101, 1, v101
	v_bitop3_b32 v101, v101, v109, 3 bitop3:0x6c
	v_lshl_or_b32 v101, v101, 4, v107
	v_cvt_pk_bf16_f32 v102, v115, s0
	v_add_u32_e32 v101, v75, v101
	ds_write_b16 v101, v102
	v_or_b32_e32 v102, 24, v108
	v_lshlrev_b32_e32 v124, 7, v102
	v_lshrrev_b32_e32 v102, 1, v102
	v_bitop3_b32 v102, v102, v109, 6 bitop3:0x6c
	v_lshl_or_b32 v102, v102, 4, v124
	v_cvt_pk_bf16_f32 v107, v116, s0
	v_add_u32_e32 v102, v75, v102
	ds_write_b16 v102, v107
	v_or_b32_e32 v107, 25, v108
	v_lshlrev_b32_e32 v125, 7, v107
	v_lshrrev_b32_e32 v107, 1, v107
	v_bitop3_b32 v107, v107, v109, 6 bitop3:0x6c
	v_or_b32_e32 v108, 26, v108
	v_lshl_or_b32 v107, v107, 4, v125
	v_lshlrev_b32_e32 v125, 7, v108
	v_lshrrev_b32_e32 v108, 1, v108
	v_bitop3_b32 v108, v108, v109, 7 bitop3:0x6c
	v_or_b32_e32 v123, 27, v123
	v_lshl_or_b32 v108, v108, 4, v125
	v_lshlrev_b32_e32 v125, 7, v123
	v_lshrrev_b32_e32 v123, 1, v123
	v_cvt_pk_bf16_f32 v124, v117, s0
	v_add_u32_e32 v107, v75, v107
	v_bitop3_b32 v109, v123, v109, 7 bitop3:0x6c
	ds_write_b16 v107, v124
	v_cvt_pk_bf16_f32 v124, v118, s0
	v_add_u32_e32 v108, v75, v108
	v_lshl_or_b32 v109, v109, 4, v125
	ds_write_b16 v108, v124
	v_cvt_pk_bf16_f32 v124, v103, s0
	v_add_u32_e32 v109, v75, v109
	v_cvt_pk_bf16_f32 v50, v50, v104
	v_cvt_pk_bf16_f32 v51, v105, v51
	ds_write_b16 v109, v124
	ds_write_b64 v85, v[50:51] offset:16384
	v_cvt_pk_bf16_f32 v50, v106, v110
	v_cvt_pk_bf16_f32 v51, v111, v112
	ds_write_b64 v86, v[50:51] offset:16384
	v_cvt_pk_bf16_f32 v50, v96, v113
	v_cvt_pk_bf16_f32 v51, v114, v115
	ds_write_b64 v87, v[50:51] offset:16384
	v_cvt_pk_bf16_f32 v50, v116, v117
	v_cvt_pk_bf16_f32 v51, v118, v103
	ds_write_b64 v88, v[50:51] offset:16384
	v_cvt_pk_bf16_f32 v50, v94, s0
	ds_write_b16 v66, v50 offset:24576
	v_cvt_pk_bf16_f32 v50, v95, s0
	ds_write_b16 v66, v50 offset:24704
	v_cvt_pk_bf16_f32 v50, v52, s0
	ds_write_b16 v68, v50 offset:24576
	v_cvt_pk_bf16_f32 v50, v53, s0
	ds_write_b16 v67, v50 offset:24576
	v_cvt_pk_bf16_f32 v50, v54, s0
	ds_write_b16 v69, v50 offset:24576
	v_cvt_pk_bf16_f32 v50, v55, s0
	ds_write_b16 v97, v50 offset:24576
	v_cvt_pk_bf16_f32 v50, v56, s0
	ds_write_b16 v98, v50 offset:24576
	v_cvt_pk_bf16_f32 v50, v57, s0
	ds_write_b16 v99, v50 offset:24576
	v_cvt_pk_bf16_f32 v50, v58, s0
	ds_write_b16 v66, v50 offset:26624
	v_cvt_pk_bf16_f32 v50, v59, s0
	ds_write_b16 v66, v50 offset:26752
	v_cvt_pk_bf16_f32 v50, v60, s0
	ds_write_b16 v100, v50 offset:24576
	v_cvt_pk_bf16_f32 v50, v61, s0
	ds_write_b16 v101, v50 offset:24576
	v_cvt_pk_bf16_f32 v50, v62, s0
	ds_write_b16 v102, v50 offset:24576
	v_cvt_pk_bf16_f32 v50, v63, s0
	v_cndmask_b32_e64 v65, 0, v65, s[36:37]
	ds_write_b16 v107, v50 offset:24576
	v_cvt_pk_bf16_f32 v50, v64, s0
	s_add_i32 s2, 0, 0x10000
	ds_write_b16 v108, v50 offset:24576
	v_cvt_pk_bf16_f32 v50, v65, s0
	v_add_u32_e32 v52, s2, v89
	v_cndmask_b32_e64 v22, v38, 0, s[10:11]
	v_cndmask_b32_e64 v23, v39, 0, s[12:13]
	ds_write_b16 v109, v50 offset:24576
	v_cvt_pk_bf16_f32 v50, v18, v19
	v_cvt_pk_bf16_f32 v51, v20, v21
	v_add_u32_e32 v103, v52, v119
	v_cndmask_b32_e64 v26, v42, 0, s[18:19]
	v_cndmask_b32_e64 v27, v43, 0, s[20:21]
	ds_write_b64 v103, v[50:51]
	v_cvt_pk_bf16_f32 v50, v22, v23
	v_cvt_pk_bf16_f32 v51, v24, v25
	v_add_u32_e32 v104, v52, v120
	v_cndmask_b32_e64 v30, v46, 0, s[26:27]
	v_cndmask_b32_e64 v31, v47, 0, s[28:29]
	ds_write_b64 v104, v[50:51]
	v_cvt_pk_bf16_f32 v50, v26, v27
	v_cvt_pk_bf16_f32 v51, v28, v29
	v_add_u32_e32 v105, v52, v121
	v_lshlrev_b32_e32 v34, 16, v36
	v_and_b32_e32 v35, 0xffff0000, v36
	v_lshlrev_b32_e32 v36, 16, v37
	v_and_b32_e32 v37, 0xffff0000, v37
	v_lshlrev_b32_e32 v38, 16, v40
	v_and_b32_e32 v39, 0xffff0000, v40
	v_lshlrev_b32_e32 v40, 16, v41
	v_and_b32_e32 v41, 0xffff0000, v41
	v_lshlrev_b32_e32 v42, 16, v44
	v_and_b32_e32 v43, 0xffff0000, v44
	v_lshlrev_b32_e32 v44, 16, v45
	v_and_b32_e32 v45, 0xffff0000, v45
	v_lshlrev_b32_e32 v46, 16, v48
	v_and_b32_e32 v47, 0xffff0000, v48
	v_lshlrev_b32_e32 v48, 16, v49
	v_and_b32_e32 v49, 0xffff0000, v49
	ds_write_b64 v105, v[50:51]
	v_cvt_pk_bf16_f32 v50, v30, v31
	v_cvt_pk_bf16_f32 v51, v32, v33
	v_add_u32_e32 v106, v52, v122
	ds_write_b64 v106, v[50:51]
	s_waitcnt lgkmcnt(0)
	s_barrier
